# A/B: every s_setprio removed from the P5 K-loop; rest as v058
# speedup vs baseline: 1.0030x; 1.0016x over previous
.LBB0_507:
	ds_read_b128 v[166:169], v163
	ds_read_b128 v[170:173], v163 offset:1024
	ds_read_b128 v[174:177], v163 offset:2048
	ds_read_b128 v[178:181], v163 offset:3072
	ds_read_b128 v[182:185], v164
	ds_read_b128 v[188:191], v164 offset:1024
	ds_read_b128 v[192:195], v164 offset:2048
	ds_read_b128 v[196:199], v164 offset:3072
	s_add_u32 s44, s42, 0xfff80080
	s_addc_u32 s45, s43, -1
	s_cmp_eq_u32 s52, 28
	s_cselect_b32 s47, s7, s45
	s_cselect_b32 s46, s6, s44
	s_cselect_b32 s45, s23, s21
	s_cselect_b32 s44, s22, s17
	s_add_u32 s54, s44, 0x80000
	s_addc_u32 s55, s45, 0
	s_mov_b32 m0, s94
	ds_read_b128 v[200:203], v165
	ds_read_b128 v[204:207], v165 offset:1024
	ds_read_b128 v[208:211], v165 offset:2048
	ds_read_b128 v[212:215], v165 offset:3072
	ds_read_b128 v[216:219], v165 offset:4096
	ds_read_b128 v[220:223], v165 offset:5120
	ds_read_b128 v[224:227], v165 offset:6144
	ds_read_b128 v[228:231], v165 offset:7168
	global_load_lds_dwordx4 v152, s[42:43]
	s_mov_b32 m0, s95
	s_nop 0
	global_load_lds_dwordx4 v154, s[42:43]
	s_waitcnt vmcnt(8)
	s_waitcnt lgkmcnt(0)
	s_barrier
	s_waitcnt lgkmcnt(0)
	v_mfma_f32_16x16x32_bf16 v[124:127], v[166:169], v[200:203], v[124:127]
	v_mfma_f32_16x16x32_bf16 v[120:123], v[174:177], v[200:203], v[120:123]
	v_mfma_f32_16x16x32_bf16 v[108:111], v[166:169], v[208:211], v[108:111]
	v_mfma_f32_16x16x32_bf16 v[104:107], v[174:177], v[208:211], v[104:107]
	v_mfma_f32_16x16x32_bf16 v[92:95], v[166:169], v[216:219], v[92:95]
	v_mfma_f32_16x16x32_bf16 v[88:91], v[174:177], v[216:219], v[88:91]
	v_mfma_f32_16x16x32_bf16 v[76:79], v[166:169], v[224:227], v[76:79]
	v_mfma_f32_16x16x32_bf16 v[72:75], v[174:177], v[224:227], v[72:75]
	v_mfma_f32_16x16x32_bf16 v[124:127], v[170:173], v[204:207], v[124:127]
	v_mfma_f32_16x16x32_bf16 v[120:123], v[178:181], v[204:207], v[120:123]
	v_mfma_f32_16x16x32_bf16 v[108:111], v[170:173], v[212:215], v[108:111]
	v_mfma_f32_16x16x32_bf16 v[104:107], v[178:181], v[212:215], v[104:107]
	v_mfma_f32_16x16x32_bf16 v[92:95], v[170:173], v[220:223], v[92:95]
	v_mfma_f32_16x16x32_bf16 v[88:91], v[178:181], v[220:223], v[88:91]
	v_mfma_f32_16x16x32_bf16 v[76:79], v[170:173], v[228:231], v[76:79]
	v_mfma_f32_16x16x32_bf16 v[72:75], v[178:181], v[228:231], v[72:75]
	v_mfma_f32_16x16x32_bf16 v[116:119], v[182:185], v[200:203], v[116:119]
	v_mfma_f32_16x16x32_bf16 v[112:115], v[192:195], v[200:203], v[112:115]
	v_mfma_f32_16x16x32_bf16 v[100:103], v[182:185], v[208:211], v[100:103]
	v_mfma_f32_16x16x32_bf16 v[96:99], v[192:195], v[208:211], v[96:99]
	v_mfma_f32_16x16x32_bf16 v[84:87], v[182:185], v[216:219], v[84:87]
	v_mfma_f32_16x16x32_bf16 v[80:83], v[192:195], v[216:219], v[80:83]
	v_mfma_f32_16x16x32_bf16 v[68:71], v[182:185], v[224:227], v[68:71]
	v_mfma_f32_16x16x32_bf16 v[64:67], v[192:195], v[224:227], v[64:67]
	v_mfma_f32_16x16x32_bf16 v[116:119], v[188:191], v[204:207], v[116:119]
	v_mfma_f32_16x16x32_bf16 v[112:115], v[196:199], v[204:207], v[112:115]
	v_mfma_f32_16x16x32_bf16 v[100:103], v[188:191], v[212:215], v[100:103]
	v_mfma_f32_16x16x32_bf16 v[96:99], v[196:199], v[212:215], v[96:99]
	v_mfma_f32_16x16x32_bf16 v[84:87], v[188:191], v[220:223], v[84:87]
	v_mfma_f32_16x16x32_bf16 v[80:83], v[196:199], v[220:223], v[80:83]
	v_mfma_f32_16x16x32_bf16 v[68:71], v[188:191], v[228:231], v[68:71]
	v_mfma_f32_16x16x32_bf16 v[64:67], v[196:199], v[228:231], v[64:67]
	s_barrier
	s_mov_b32 m0, s96
	s_add_u32 s98, s46, 0x80000
	s_addc_u32 s99, s47, 0
	ds_read_b128 v[200:203], v165 offset:16384
	ds_read_b128 v[204:207], v165 offset:17408
	ds_read_b128 v[208:211], v165 offset:18432
	ds_read_b128 v[212:215], v165 offset:19456
	ds_read_b128 v[216:219], v165 offset:20480
	ds_read_b128 v[220:223], v165 offset:21504
	ds_read_b128 v[224:227], v165 offset:22528
	ds_read_b128 v[228:231], v165 offset:23552
	global_load_lds_dwordx4 v130, s[44:45]
	s_mov_b32 m0, s97
	s_nop 0
	global_load_lds_dwordx4 v134, s[44:45]
	s_mov_b32 m0, s91
	s_nop 0
	global_load_lds_dwordx4 v130, s[54:55]
	s_mov_b32 m0, s26
	s_nop 0
	global_load_lds_dwordx4 v134, s[54:55]
	s_mov_b32 m0, s33
	s_nop 0
	global_load_lds_dwordx4 v128, s[46:47]
	s_mov_b32 m0, s88
	s_nop 0
	global_load_lds_dwordx4 v132, s[46:47]
	s_waitcnt vmcnt(8)
	s_waitcnt lgkmcnt(0)
	s_barrier
	s_waitcnt lgkmcnt(0)
	v_mfma_f32_16x16x32_bf16 v[60:63], v[166:169], v[200:203], v[60:63]
	v_mfma_f32_16x16x32_bf16 v[56:59], v[174:177], v[200:203], v[56:59]
	v_mfma_f32_16x16x32_bf16 v[44:47], v[166:169], v[208:211], v[44:47]
	v_mfma_f32_16x16x32_bf16 v[40:43], v[174:177], v[208:211], v[40:43]
	v_mfma_f32_16x16x32_bf16 v[28:31], v[166:169], v[216:219], v[28:31]
	v_mfma_f32_16x16x32_bf16 v[24:27], v[174:177], v[216:219], v[24:27]
	v_mfma_f32_16x16x32_bf16 v[12:15], v[166:169], v[224:227], v[12:15]
	v_mfma_f32_16x16x32_bf16 v[8:11], v[174:177], v[224:227], v[8:11]
	v_mfma_f32_16x16x32_bf16 v[60:63], v[170:173], v[204:207], v[60:63]
	v_mfma_f32_16x16x32_bf16 v[56:59], v[178:181], v[204:207], v[56:59]
	v_mfma_f32_16x16x32_bf16 v[44:47], v[170:173], v[212:215], v[44:47]
	v_mfma_f32_16x16x32_bf16 v[40:43], v[178:181], v[212:215], v[40:43]
	v_mfma_f32_16x16x32_bf16 v[28:31], v[170:173], v[220:223], v[28:31]
	v_mfma_f32_16x16x32_bf16 v[24:27], v[178:181], v[220:223], v[24:27]
	v_mfma_f32_16x16x32_bf16 v[12:15], v[170:173], v[228:231], v[12:15]
	v_mfma_f32_16x16x32_bf16 v[8:11], v[178:181], v[228:231], v[8:11]
	v_mfma_f32_16x16x32_bf16 v[52:55], v[182:185], v[200:203], v[52:55]
	v_mfma_f32_16x16x32_bf16 v[48:51], v[192:195], v[200:203], v[48:51]
	v_mfma_f32_16x16x32_bf16 v[36:39], v[182:185], v[208:211], v[36:39]
	v_mfma_f32_16x16x32_bf16 v[32:35], v[192:195], v[208:211], v[32:35]
	v_mfma_f32_16x16x32_bf16 v[20:23], v[182:185], v[216:219], v[20:23]
	v_mfma_f32_16x16x32_bf16 v[16:19], v[192:195], v[216:219], v[16:19]
	v_mfma_f32_16x16x32_bf16 v[4:7], v[182:185], v[224:227], v[4:7]
	v_mfma_f32_16x16x32_bf16 v[0:3], v[192:195], v[224:227], v[0:3]
	v_mfma_f32_16x16x32_bf16 v[52:55], v[188:191], v[204:207], v[52:55]
	v_mfma_f32_16x16x32_bf16 v[48:51], v[196:199], v[204:207], v[48:51]
	v_mfma_f32_16x16x32_bf16 v[36:39], v[188:191], v[212:215], v[36:39]
	v_mfma_f32_16x16x32_bf16 v[32:35], v[196:199], v[212:215], v[32:35]
	v_mfma_f32_16x16x32_bf16 v[20:23], v[188:191], v[220:223], v[20:23]
	v_mfma_f32_16x16x32_bf16 v[16:19], v[196:199], v[220:223], v[16:19]
	v_mfma_f32_16x16x32_bf16 v[4:7], v[188:191], v[228:231], v[4:7]
	v_mfma_f32_16x16x32_bf16 v[0:3], v[196:199], v[228:231], v[0:3]
	s_barrier
	v_add_u32_e32 v178, s29, v162
	v_add_u32_e32 v187, s41, v162
	ds_read_b128 v[166:169], v178
	ds_read_b128 v[170:173], v178 offset:1024
	ds_read_b128 v[174:177], v178 offset:2048
	ds_read_b128 v[178:181], v178 offset:3072
	ds_read_b128 v[182:185], v187
	ds_read_b128 v[188:191], v187 offset:1024
	ds_read_b128 v[192:195], v187 offset:2048
	ds_read_b128 v[196:199], v187 offset:3072
	s_mov_b32 m0, s89
	s_add_u32 s100, s44, 0x80
	s_addc_u32 s101, s45, 0
	ds_read_b128 v[200:203], v165 offset:32768
	ds_read_b128 v[204:207], v165 offset:33792
	ds_read_b128 v[208:211], v165 offset:34816
	ds_read_b128 v[212:215], v165 offset:35840
	ds_read_b128 v[216:219], v165 offset:36864
	ds_read_b128 v[220:223], v165 offset:37888
	ds_read_b128 v[224:227], v165 offset:38912
	ds_read_b128 v[228:231], v165 offset:39936
	global_load_lds_dwordx4 v128, s[98:99]
	s_mov_b32 m0, s90
	s_add_u32 s54, s44, 0x80080
	s_addc_u32 s55, s45, 0
	global_load_lds_dwordx4 v132, s[98:99]
	s_add_u32 s98, s46, 0x80
	s_addc_u32 s99, s47, 0
	s_waitcnt vmcnt(8)
	s_waitcnt lgkmcnt(0)
	s_barrier
	s_waitcnt lgkmcnt(0)
	v_mfma_f32_16x16x32_bf16 v[124:127], v[166:169], v[200:203], v[124:127]
	v_mfma_f32_16x16x32_bf16 v[120:123], v[174:177], v[200:203], v[120:123]
	v_mfma_f32_16x16x32_bf16 v[108:111], v[166:169], v[208:211], v[108:111]
	v_mfma_f32_16x16x32_bf16 v[104:107], v[174:177], v[208:211], v[104:107]
	v_mfma_f32_16x16x32_bf16 v[92:95], v[166:169], v[216:219], v[92:95]
	v_mfma_f32_16x16x32_bf16 v[88:91], v[174:177], v[216:219], v[88:91]
	v_mfma_f32_16x16x32_bf16 v[76:79], v[166:169], v[224:227], v[76:79]
	v_mfma_f32_16x16x32_bf16 v[72:75], v[174:177], v[224:227], v[72:75]
	v_mfma_f32_16x16x32_bf16 v[124:127], v[170:173], v[204:207], v[124:127]
	v_mfma_f32_16x16x32_bf16 v[120:123], v[178:181], v[204:207], v[120:123]
	v_mfma_f32_16x16x32_bf16 v[108:111], v[170:173], v[212:215], v[108:111]
	v_mfma_f32_16x16x32_bf16 v[104:107], v[178:181], v[212:215], v[104:107]
	v_mfma_f32_16x16x32_bf16 v[92:95], v[170:173], v[220:223], v[92:95]
	v_mfma_f32_16x16x32_bf16 v[88:91], v[178:181], v[220:223], v[88:91]
	v_mfma_f32_16x16x32_bf16 v[76:79], v[170:173], v[228:231], v[76:79]
	v_mfma_f32_16x16x32_bf16 v[72:75], v[178:181], v[228:231], v[72:75]
	v_mfma_f32_16x16x32_bf16 v[116:119], v[182:185], v[200:203], v[116:119]
	v_mfma_f32_16x16x32_bf16 v[112:115], v[192:195], v[200:203], v[112:115]
	v_mfma_f32_16x16x32_bf16 v[100:103], v[182:185], v[208:211], v[100:103]
	v_mfma_f32_16x16x32_bf16 v[96:99], v[192:195], v[208:211], v[96:99]
	v_mfma_f32_16x16x32_bf16 v[84:87], v[182:185], v[216:219], v[84:87]
	v_mfma_f32_16x16x32_bf16 v[80:83], v[192:195], v[216:219], v[80:83]
	v_mfma_f32_16x16x32_bf16 v[68:71], v[182:185], v[224:227], v[68:71]
	v_mfma_f32_16x16x32_bf16 v[64:67], v[192:195], v[224:227], v[64:67]
	v_mfma_f32_16x16x32_bf16 v[116:119], v[188:191], v[204:207], v[116:119]
	v_mfma_f32_16x16x32_bf16 v[112:115], v[196:199], v[204:207], v[112:115]
	v_mfma_f32_16x16x32_bf16 v[100:103], v[188:191], v[212:215], v[100:103]
	v_mfma_f32_16x16x32_bf16 v[96:99], v[196:199], v[212:215], v[96:99]
	v_mfma_f32_16x16x32_bf16 v[84:87], v[188:191], v[220:223], v[84:87]
	v_mfma_f32_16x16x32_bf16 v[80:83], v[196:199], v[220:223], v[80:83]
	v_mfma_f32_16x16x32_bf16 v[68:71], v[188:191], v[228:231], v[68:71]
	v_mfma_f32_16x16x32_bf16 v[64:67], v[196:199], v[228:231], v[64:67]
	s_barrier
	s_mov_b32 m0, s27
	s_nop 0
	ds_read_b128 v[200:203], v165 offset:49152
	ds_read_b128 v[204:207], v165 offset:50176
	ds_read_b128 v[208:211], v165 offset:51200
	ds_read_b128 v[212:215], v165 offset:52224
	ds_read_b128 v[216:219], v165 offset:53248
	ds_read_b128 v[220:223], v165 offset:54272
	ds_read_b128 v[224:227], v165 offset:55296
	ds_read_b128 v[228:231], v165 offset:56320
	global_load_lds_dwordx4 v130, s[100:101]
	s_mov_b32 m0, s34
	s_nop 0
	global_load_lds_dwordx4 v134, s[100:101]
	s_mov_b32 m0, s35
	s_nop 0
	global_load_lds_dwordx4 v130, s[54:55]
	s_mov_b32 m0, s28
	s_nop 0
	global_load_lds_dwordx4 v134, s[54:55]
	s_mov_b32 m0, s92
	s_nop 0
	global_load_lds_dwordx4 v128, s[98:99]
	s_mov_b32 m0, s93
	s_nop 0
	global_load_lds_dwordx4 v132, s[98:99]
	s_waitcnt vmcnt(8)
	s_waitcnt lgkmcnt(0)
	s_barrier
	s_waitcnt lgkmcnt(0)
	v_mfma_f32_16x16x32_bf16 v[60:63], v[166:169], v[200:203], v[60:63]
	v_mfma_f32_16x16x32_bf16 v[56:59], v[174:177], v[200:203], v[56:59]
	v_mfma_f32_16x16x32_bf16 v[44:47], v[166:169], v[208:211], v[44:47]
	v_mfma_f32_16x16x32_bf16 v[40:43], v[174:177], v[208:211], v[40:43]
	v_mfma_f32_16x16x32_bf16 v[28:31], v[166:169], v[216:219], v[28:31]
	v_mfma_f32_16x16x32_bf16 v[24:27], v[174:177], v[216:219], v[24:27]
	v_mfma_f32_16x16x32_bf16 v[12:15], v[166:169], v[224:227], v[12:15]
	v_mfma_f32_16x16x32_bf16 v[8:11], v[174:177], v[224:227], v[8:11]
	v_mfma_f32_16x16x32_bf16 v[60:63], v[170:173], v[204:207], v[60:63]
	v_mfma_f32_16x16x32_bf16 v[56:59], v[178:181], v[204:207], v[56:59]
	v_mfma_f32_16x16x32_bf16 v[44:47], v[170:173], v[212:215], v[44:47]
	v_mfma_f32_16x16x32_bf16 v[40:43], v[178:181], v[212:215], v[40:43]
	v_mfma_f32_16x16x32_bf16 v[28:31], v[170:173], v[220:223], v[28:31]
	v_mfma_f32_16x16x32_bf16 v[24:27], v[178:181], v[220:223], v[24:27]
	v_mfma_f32_16x16x32_bf16 v[12:15], v[170:173], v[228:231], v[12:15]
	v_mfma_f32_16x16x32_bf16 v[8:11], v[178:181], v[228:231], v[8:11]
	v_mfma_f32_16x16x32_bf16 v[52:55], v[182:185], v[200:203], v[52:55]
	v_mfma_f32_16x16x32_bf16 v[48:51], v[192:195], v[200:203], v[48:51]
	v_mfma_f32_16x16x32_bf16 v[36:39], v[182:185], v[208:211], v[36:39]
	v_mfma_f32_16x16x32_bf16 v[32:35], v[192:195], v[208:211], v[32:35]
	v_mfma_f32_16x16x32_bf16 v[20:23], v[182:185], v[216:219], v[20:23]
	v_mfma_f32_16x16x32_bf16 v[16:19], v[192:195], v[216:219], v[16:19]
	v_mfma_f32_16x16x32_bf16 v[4:7], v[182:185], v[224:227], v[4:7]
	v_mfma_f32_16x16x32_bf16 v[0:3], v[192:195], v[224:227], v[0:3]
	v_mfma_f32_16x16x32_bf16 v[52:55], v[188:191], v[204:207], v[52:55]
	v_mfma_f32_16x16x32_bf16 v[48:51], v[196:199], v[204:207], v[48:51]
	v_mfma_f32_16x16x32_bf16 v[36:39], v[188:191], v[212:215], v[36:39]
	v_mfma_f32_16x16x32_bf16 v[32:35], v[196:199], v[212:215], v[32:35]
	v_mfma_f32_16x16x32_bf16 v[20:23], v[188:191], v[220:223], v[20:23]
	v_mfma_f32_16x16x32_bf16 v[16:19], v[196:199], v[220:223], v[16:19]
	v_mfma_f32_16x16x32_bf16 v[4:7], v[188:191], v[228:231], v[4:7]
	v_mfma_f32_16x16x32_bf16 v[0:3], v[196:199], v[228:231], v[0:3]
	s_barrier
	s_add_i32 s52, s52, 2
	s_add_u32 s42, s42, 0x100
	s_addc_u32 s43, s43, 0
	s_add_u32 s17, s17, 0x100
	s_addc_u32 s21, s21, 0
	s_cmp_gt_u32 s52, 29
	s_cbranch_scc0 .LBB0_507
	s_and_b64 vcc, exec, s[78:79]
	s_cbranch_vccz .LBB0_510
	s_barrier
